# P0 channel-DFT fold item: per-wave 128-entry twiddle table in LDS + LDS-DMA staged operand instead of 64 in-loop sincospif evaluations
# speedup vs baseline: 1.0107x; 1.0107x over previous
.LBB0_1866:
	s_lshl_b32 s4, s84, 14
	s_lshl_b32 s5, s84, 9
	s_add_i32 s5, s5, 0x20000
	v_readfirstlane_b32 s6, v22
	v_readfirstlane_b32 s7, v23
	v_lshrrev_b32_e32 v39, 4, v68
	v_bfe_u32 v40, v68, 3, 1
	v_and_b32_e32 v41, 7, v68
	v_lshlrev_b32_e32 v39, 13, v39
	v_lshl_or_b32 v39, v40, 12, v39
	v_lshl_or_b32 v39, v41, 4, v39
	s_add_u32 s6, s6, 0x400000
	s_addc_u32 s7, s7, 0
	s_mov_b32 m0, s4
	s_nop 0
	global_load_lds_dwordx4 v39, s[6:7]
	v_add_u32_e32 v39, 0x8000, v39
	s_add_i32 m0, s4, 0x400
	s_nop 0
	global_load_lds_dwordx4 v39, s[6:7]
	v_add_u32_e32 v39, 0x8000, v39
	s_add_i32 m0, s4, 0x800
	s_nop 0
	global_load_lds_dwordx4 v39, s[6:7]
	v_add_u32_e32 v39, 0x8000, v39
	s_add_i32 m0, s4, 0xc00
	s_nop 0
	global_load_lds_dwordx4 v39, s[6:7]
	v_add_u32_e32 v39, 0x8000, v39
	s_add_i32 m0, s4, 0x1000
	s_nop 0
	global_load_lds_dwordx4 v39, s[6:7]
	v_add_u32_e32 v39, 0x8000, v39
	s_add_i32 m0, s4, 0x1400
	s_nop 0
	global_load_lds_dwordx4 v39, s[6:7]
	v_add_u32_e32 v39, 0x8000, v39
	s_add_i32 m0, s4, 0x1800
	s_nop 0
	global_load_lds_dwordx4 v39, s[6:7]
	v_add_u32_e32 v39, 0x8000, v39
	s_add_i32 m0, s4, 0x1c00
	s_nop 0
	global_load_lds_dwordx4 v39, s[6:7]
	v_add_u32_e32 v39, 0x8000, v39
	s_add_i32 m0, s4, 0x2000
	s_nop 0
	global_load_lds_dwordx4 v39, s[6:7]
	v_add_u32_e32 v39, 0x8000, v39
	s_add_i32 m0, s4, 0x2400
	s_nop 0
	global_load_lds_dwordx4 v39, s[6:7]
	v_add_u32_e32 v39, 0x8000, v39
	s_add_i32 m0, s4, 0x2800
	s_nop 0
	global_load_lds_dwordx4 v39, s[6:7]
	v_add_u32_e32 v39, 0x8000, v39
	s_add_i32 m0, s4, 0x2c00
	s_nop 0
	global_load_lds_dwordx4 v39, s[6:7]
	v_add_u32_e32 v39, 0x8000, v39
	s_add_i32 m0, s4, 0x3000
	s_nop 0
	global_load_lds_dwordx4 v39, s[6:7]
	v_add_u32_e32 v39, 0x8000, v39
	s_add_i32 m0, s4, 0x3400
	s_nop 0
	global_load_lds_dwordx4 v39, s[6:7]
	v_add_u32_e32 v39, 0x8000, v39
	s_add_i32 m0, s4, 0x3800
	s_nop 0
	global_load_lds_dwordx4 v39, s[6:7]
	v_add_u32_e32 v39, 0x8000, v39
	s_add_i32 m0, s4, 0x3c00
	s_nop 0
	global_load_lds_dwordx4 v39, s[6:7]
	s_cmpk_lt_u32 s27, 0x200
	s_cselect_b64 vcc, -1, 0
	v_lshl_add_u32 v38, v68, 2, s5
	v_mov_b32_e32 v49, v68
	v_cvt_f32_ubyte0_e32 v58, v49
	v_mul_f32_e32 v58, 0x3c800000, v58
	v_mul_f32_e32 v50, 0.5, v58
	v_fract_f32_e32 v60, v50
	v_cmp_neq_f32_e64 s[66:67], s30, v50
	v_add_f32_e32 v57, v60, v60
	v_cmp_lt_f32_e64 s[50:51], 1.0, v58
	s_nop 1
	v_cndmask_b32_e64 v57, 0, v57, s[66:67]
	s_nop 0
	v_cndmask_b32_e64 v57, v58, v57, s[50:51]
	v_add_f32_e32 v45, v57, v57
	v_rndne_f32_e32 v45, v45
	v_fmac_f32_e32 v57, -0.5, v45
	v_mul_f32_e32 v62, v57, v57
	v_cvt_i32_f32_e32 v60, v45
	v_fmamk_f32 v73, v62, 0x3e75aa41, v199
	v_fmamk_f32 v75, v62, 0x3d4be544, v200
	v_fmaak_f32 v73, v62, v73, 0x40234736
	v_mul_f32_e32 v74, v57, v62
	v_fmaak_f32 v75, v62, v75, 0xbfaad1da
	v_fmaak_f32 v73, v62, v73, 0xc0a55e0e
	v_fmaak_f32 v75, v62, v75, 0x4081e0d3
	v_mul_f32_e32 v73, v74, v73
	v_lshlrev_b32_e32 v96, 30, v60
	v_and_b32_e32 v60, 1, v60
	v_fmaak_f32 v74, v62, v75, 0xc09de9e6
	v_fmac_f32_e32 v73, 0x40490fdb, v57
	v_cmp_eq_u32_e64 s[50:51], 0, v60
	v_fma_f32 v57, v62, v74, 1.0
	v_xor_b32_e32 v62, 0x80000000, v73
	s_nop 0
	v_cndmask_b32_e64 v60, v57, v73, s[50:51]
	v_cndmask_b32_e64 v57, v62, v57, s[50:51]
	v_cmp_lg_f32_e64 s[48:49], s30, v58
	v_bitop3_b32 v60, v60, v96, s33 bitop3:0x78
	v_bitop3_b32 v57, v57, v96, s33 bitop3:0x78
	s_nop 0
	v_cndmask_b32_e64 v60, v213, -v60, s[48:49]
	v_cndmask_b32_e64 v57, v212, v57, s[48:49]
	s_nop 0
	v_cndmask_b32_e32 v57, v60, v57, vcc
	v_mul_f32_e32 v57, 0x3db504f3, v57
	ds_write_b32 v38, v57
	v_add_u32_e32 v49, 64, v68
	v_cvt_f32_ubyte0_e32 v58, v49
	v_mul_f32_e32 v58, 0x3c800000, v58
	v_mul_f32_e32 v50, 0.5, v58
	v_fract_f32_e32 v60, v50
	v_cmp_neq_f32_e64 s[66:67], s30, v50
	v_add_f32_e32 v57, v60, v60
	v_cmp_lt_f32_e64 s[50:51], 1.0, v58
	s_nop 1
	v_cndmask_b32_e64 v57, 0, v57, s[66:67]
	s_nop 0
	v_cndmask_b32_e64 v57, v58, v57, s[50:51]
	v_add_f32_e32 v45, v57, v57
	v_rndne_f32_e32 v45, v45
	v_fmac_f32_e32 v57, -0.5, v45
	v_mul_f32_e32 v62, v57, v57
	v_cvt_i32_f32_e32 v60, v45
	v_fmamk_f32 v73, v62, 0x3e75aa41, v199
	v_fmamk_f32 v75, v62, 0x3d4be544, v200
	v_fmaak_f32 v73, v62, v73, 0x40234736
	v_mul_f32_e32 v74, v57, v62
	v_fmaak_f32 v75, v62, v75, 0xbfaad1da
	v_fmaak_f32 v73, v62, v73, 0xc0a55e0e
	v_fmaak_f32 v75, v62, v75, 0x4081e0d3
	v_mul_f32_e32 v73, v74, v73
	v_lshlrev_b32_e32 v96, 30, v60
	v_and_b32_e32 v60, 1, v60
	v_fmaak_f32 v74, v62, v75, 0xc09de9e6
	v_fmac_f32_e32 v73, 0x40490fdb, v57
	v_cmp_eq_u32_e64 s[50:51], 0, v60
	v_fma_f32 v57, v62, v74, 1.0
	v_xor_b32_e32 v62, 0x80000000, v73
	s_nop 0
	v_cndmask_b32_e64 v60, v57, v73, s[50:51]
	v_cndmask_b32_e64 v57, v62, v57, s[50:51]
	v_cmp_lg_f32_e64 s[48:49], s30, v58
	v_bitop3_b32 v60, v60, v96, s33 bitop3:0x78
	v_bitop3_b32 v57, v57, v96, s33 bitop3:0x78
	s_nop 0
	v_cndmask_b32_e64 v60, v213, -v60, s[48:49]
	v_cndmask_b32_e64 v57, v212, v57, s[48:49]
	s_nop 0
	v_cndmask_b32_e32 v57, v60, v57, vcc
	v_mul_f32_e32 v57, 0x3db504f3, v57
	ds_write_b32 v38, v57 offset:256
	v_lshl_add_u32 v40, v68, 2, s4
	v_lshrrev_b32_e32 v41, 3, v29
	v_mov_b32_e32 v42, v37
	s_waitcnt vmcnt(0) lgkmcnt(0)
	ds_read_b32 v43, v40 offset:0
	v_and_b32_e32 v59, 0x7f, v42
	v_lshl_add_u32 v59, v59, 2, s5
	ds_read_b32 v51, v59
	v_add_u32_e32 v42, v42, v41
	ds_read_b32 v44, v40 offset:256
	v_and_b32_e32 v59, 0x7f, v42
	v_lshl_add_u32 v59, v59, 2, s5
	ds_read_b32 v52, v59
	v_add_u32_e32 v42, v42, v41
	ds_read_b32 v45, v40 offset:512
	v_and_b32_e32 v59, 0x7f, v42
	v_lshl_add_u32 v59, v59, 2, s5
	ds_read_b32 v53, v59
	v_add_u32_e32 v42, v42, v41
	ds_read_b32 v46, v40 offset:768
	v_and_b32_e32 v59, 0x7f, v42
	v_lshl_add_u32 v59, v59, 2, s5
	ds_read_b32 v54, v59
	v_add_u32_e32 v42, v42, v41
	ds_read_b32 v47, v40 offset:1024
	v_and_b32_e32 v59, 0x7f, v42
	v_lshl_add_u32 v59, v59, 2, s5
	ds_read_b32 v55, v59
	v_add_u32_e32 v42, v42, v41
	ds_read_b32 v48, v40 offset:1280
	v_and_b32_e32 v59, 0x7f, v42
	v_lshl_add_u32 v59, v59, 2, s5
	ds_read_b32 v56, v59
	v_add_u32_e32 v42, v42, v41
	ds_read_b32 v49, v40 offset:1536
	v_and_b32_e32 v59, 0x7f, v42
	v_lshl_add_u32 v59, v59, 2, s5
	ds_read_b32 v57, v59
	v_add_u32_e32 v42, v42, v41
	ds_read_b32 v50, v40 offset:1792
	v_and_b32_e32 v59, 0x7f, v42
	v_lshl_add_u32 v59, v59, 2, s5
	ds_read_b32 v58, v59
	v_add_u32_e32 v42, v42, v41
	s_waitcnt lgkmcnt(8)
	v_mfma_f32_32x32x2_f32 v[4:19], v43, v51, v[4:19]
	v_mfma_f32_32x32x2_f32 v[4:19], v44, v52, v[4:19]
	v_mfma_f32_32x32x2_f32 v[4:19], v45, v53, v[4:19]
	v_mfma_f32_32x32x2_f32 v[4:19], v46, v54, v[4:19]
	ds_read_b32 v43, v40 offset:2048
	v_and_b32_e32 v59, 0x7f, v42
	v_lshl_add_u32 v59, v59, 2, s5
	ds_read_b32 v51, v59
	v_add_u32_e32 v42, v42, v41
	ds_read_b32 v44, v40 offset:2304
	v_and_b32_e32 v59, 0x7f, v42
	v_lshl_add_u32 v59, v59, 2, s5
	ds_read_b32 v52, v59
	v_add_u32_e32 v42, v42, v41
	ds_read_b32 v45, v40 offset:2560
	v_and_b32_e32 v59, 0x7f, v42
	v_lshl_add_u32 v59, v59, 2, s5
	ds_read_b32 v53, v59
	v_add_u32_e32 v42, v42, v41
	ds_read_b32 v46, v40 offset:2816
	v_and_b32_e32 v59, 0x7f, v42
	v_lshl_add_u32 v59, v59, 2, s5
	ds_read_b32 v54, v59
	v_add_u32_e32 v42, v42, v41
	s_waitcnt lgkmcnt(8)
	v_mfma_f32_32x32x2_f32 v[4:19], v47, v55, v[4:19]
	v_mfma_f32_32x32x2_f32 v[4:19], v48, v56, v[4:19]
	v_mfma_f32_32x32x2_f32 v[4:19], v49, v57, v[4:19]
	v_mfma_f32_32x32x2_f32 v[4:19], v50, v58, v[4:19]
	ds_read_b32 v47, v40 offset:3072
	v_and_b32_e32 v59, 0x7f, v42
	v_lshl_add_u32 v59, v59, 2, s5
	ds_read_b32 v55, v59
	v_add_u32_e32 v42, v42, v41
	ds_read_b32 v48, v40 offset:3328
	v_and_b32_e32 v59, 0x7f, v42
	v_lshl_add_u32 v59, v59, 2, s5
	ds_read_b32 v56, v59
	v_add_u32_e32 v42, v42, v41
	ds_read_b32 v49, v40 offset:3584
	v_and_b32_e32 v59, 0x7f, v42
	v_lshl_add_u32 v59, v59, 2, s5
	ds_read_b32 v57, v59
	v_add_u32_e32 v42, v42, v41
	ds_read_b32 v50, v40 offset:3840
	v_and_b32_e32 v59, 0x7f, v42
	v_lshl_add_u32 v59, v59, 2, s5
	ds_read_b32 v58, v59
	v_add_u32_e32 v42, v42, v41
	s_waitcnt lgkmcnt(8)
	v_mfma_f32_32x32x2_f32 v[4:19], v43, v51, v[4:19]
	v_mfma_f32_32x32x2_f32 v[4:19], v44, v52, v[4:19]
	v_mfma_f32_32x32x2_f32 v[4:19], v45, v53, v[4:19]
	v_mfma_f32_32x32x2_f32 v[4:19], v46, v54, v[4:19]
	ds_read_b32 v43, v40 offset:4096
	v_and_b32_e32 v59, 0x7f, v42
	v_lshl_add_u32 v59, v59, 2, s5
	ds_read_b32 v51, v59
	v_add_u32_e32 v42, v42, v41
	ds_read_b32 v44, v40 offset:4352
	v_and_b32_e32 v59, 0x7f, v42
	v_lshl_add_u32 v59, v59, 2, s5
	ds_read_b32 v52, v59
	v_add_u32_e32 v42, v42, v41
	ds_read_b32 v45, v40 offset:4608
	v_and_b32_e32 v59, 0x7f, v42
	v_lshl_add_u32 v59, v59, 2, s5
	ds_read_b32 v53, v59
	v_add_u32_e32 v42, v42, v41
	ds_read_b32 v46, v40 offset:4864
	v_and_b32_e32 v59, 0x7f, v42
	v_lshl_add_u32 v59, v59, 2, s5
	ds_read_b32 v54, v59
	v_add_u32_e32 v42, v42, v41
	s_waitcnt lgkmcnt(8)
	v_mfma_f32_32x32x2_f32 v[4:19], v47, v55, v[4:19]
	v_mfma_f32_32x32x2_f32 v[4:19], v48, v56, v[4:19]
	v_mfma_f32_32x32x2_f32 v[4:19], v49, v57, v[4:19]
	v_mfma_f32_32x32x2_f32 v[4:19], v50, v58, v[4:19]
	ds_read_b32 v47, v40 offset:5120
	v_and_b32_e32 v59, 0x7f, v42
	v_lshl_add_u32 v59, v59, 2, s5
	ds_read_b32 v55, v59
	v_add_u32_e32 v42, v42, v41
	ds_read_b32 v48, v40 offset:5376
	v_and_b32_e32 v59, 0x7f, v42
	v_lshl_add_u32 v59, v59, 2, s5
	ds_read_b32 v56, v59
	v_add_u32_e32 v42, v42, v41
	ds_read_b32 v49, v40 offset:5632
	v_and_b32_e32 v59, 0x7f, v42
	v_lshl_add_u32 v59, v59, 2, s5
	ds_read_b32 v57, v59
	v_add_u32_e32 v42, v42, v41
	ds_read_b32 v50, v40 offset:5888
	v_and_b32_e32 v59, 0x7f, v42
	v_lshl_add_u32 v59, v59, 2, s5
	ds_read_b32 v58, v59
	v_add_u32_e32 v42, v42, v41
	s_waitcnt lgkmcnt(8)
	v_mfma_f32_32x32x2_f32 v[4:19], v43, v51, v[4:19]
	v_mfma_f32_32x32x2_f32 v[4:19], v44, v52, v[4:19]
	v_mfma_f32_32x32x2_f32 v[4:19], v45, v53, v[4:19]
	v_mfma_f32_32x32x2_f32 v[4:19], v46, v54, v[4:19]
	ds_read_b32 v43, v40 offset:6144
	v_and_b32_e32 v59, 0x7f, v42
	v_lshl_add_u32 v59, v59, 2, s5
	ds_read_b32 v51, v59
	v_add_u32_e32 v42, v42, v41
	ds_read_b32 v44, v40 offset:6400
	v_and_b32_e32 v59, 0x7f, v42
	v_lshl_add_u32 v59, v59, 2, s5
	ds_read_b32 v52, v59
	v_add_u32_e32 v42, v42, v41
	ds_read_b32 v45, v40 offset:6656
	v_and_b32_e32 v59, 0x7f, v42
	v_lshl_add_u32 v59, v59, 2, s5
	ds_read_b32 v53, v59
	v_add_u32_e32 v42, v42, v41
	ds_read_b32 v46, v40 offset:6912
	v_and_b32_e32 v59, 0x7f, v42
	v_lshl_add_u32 v59, v59, 2, s5
	ds_read_b32 v54, v59
	v_add_u32_e32 v42, v42, v41
	s_waitcnt lgkmcnt(8)
	v_mfma_f32_32x32x2_f32 v[4:19], v47, v55, v[4:19]
	v_mfma_f32_32x32x2_f32 v[4:19], v48, v56, v[4:19]
	v_mfma_f32_32x32x2_f32 v[4:19], v49, v57, v[4:19]
	v_mfma_f32_32x32x2_f32 v[4:19], v50, v58, v[4:19]
	ds_read_b32 v47, v40 offset:7168
	v_and_b32_e32 v59, 0x7f, v42
	v_lshl_add_u32 v59, v59, 2, s5
	ds_read_b32 v55, v59
	v_add_u32_e32 v42, v42, v41
	ds_read_b32 v48, v40 offset:7424
	v_and_b32_e32 v59, 0x7f, v42
	v_lshl_add_u32 v59, v59, 2, s5
	ds_read_b32 v56, v59
	v_add_u32_e32 v42, v42, v41
	ds_read_b32 v49, v40 offset:7680
	v_and_b32_e32 v59, 0x7f, v42
	v_lshl_add_u32 v59, v59, 2, s5
	ds_read_b32 v57, v59
	v_add_u32_e32 v42, v42, v41
	ds_read_b32 v50, v40 offset:7936
	v_and_b32_e32 v59, 0x7f, v42
	v_lshl_add_u32 v59, v59, 2, s5
	ds_read_b32 v58, v59
	v_add_u32_e32 v42, v42, v41
	s_waitcnt lgkmcnt(8)
	v_mfma_f32_32x32x2_f32 v[4:19], v43, v51, v[4:19]
	v_mfma_f32_32x32x2_f32 v[4:19], v44, v52, v[4:19]
	v_mfma_f32_32x32x2_f32 v[4:19], v45, v53, v[4:19]
	v_mfma_f32_32x32x2_f32 v[4:19], v46, v54, v[4:19]
	ds_read_b32 v43, v40 offset:8192
	v_and_b32_e32 v59, 0x7f, v42
	v_lshl_add_u32 v59, v59, 2, s5
	ds_read_b32 v51, v59
	v_add_u32_e32 v42, v42, v41
	ds_read_b32 v44, v40 offset:8448
	v_and_b32_e32 v59, 0x7f, v42
	v_lshl_add_u32 v59, v59, 2, s5
	ds_read_b32 v52, v59
	v_add_u32_e32 v42, v42, v41
	ds_read_b32 v45, v40 offset:8704
	v_and_b32_e32 v59, 0x7f, v42
	v_lshl_add_u32 v59, v59, 2, s5
	ds_read_b32 v53, v59
	v_add_u32_e32 v42, v42, v41
	ds_read_b32 v46, v40 offset:8960
	v_and_b32_e32 v59, 0x7f, v42
	v_lshl_add_u32 v59, v59, 2, s5
	ds_read_b32 v54, v59
	v_add_u32_e32 v42, v42, v41
	s_waitcnt lgkmcnt(8)
	v_mfma_f32_32x32x2_f32 v[4:19], v47, v55, v[4:19]
	v_mfma_f32_32x32x2_f32 v[4:19], v48, v56, v[4:19]
	v_mfma_f32_32x32x2_f32 v[4:19], v49, v57, v[4:19]
	v_mfma_f32_32x32x2_f32 v[4:19], v50, v58, v[4:19]
	ds_read_b32 v47, v40 offset:9216
	v_and_b32_e32 v59, 0x7f, v42
	v_lshl_add_u32 v59, v59, 2, s5
	ds_read_b32 v55, v59
	v_add_u32_e32 v42, v42, v41
	ds_read_b32 v48, v40 offset:9472
	v_and_b32_e32 v59, 0x7f, v42
	v_lshl_add_u32 v59, v59, 2, s5
	ds_read_b32 v56, v59
	v_add_u32_e32 v42, v42, v41
	ds_read_b32 v49, v40 offset:9728
	v_and_b32_e32 v59, 0x7f, v42
	v_lshl_add_u32 v59, v59, 2, s5
	ds_read_b32 v57, v59
	v_add_u32_e32 v42, v42, v41
	ds_read_b32 v50, v40 offset:9984
	v_and_b32_e32 v59, 0x7f, v42
	v_lshl_add_u32 v59, v59, 2, s5
	ds_read_b32 v58, v59
	v_add_u32_e32 v42, v42, v41
	s_waitcnt lgkmcnt(8)
	v_mfma_f32_32x32x2_f32 v[4:19], v43, v51, v[4:19]
	v_mfma_f32_32x32x2_f32 v[4:19], v44, v52, v[4:19]
	v_mfma_f32_32x32x2_f32 v[4:19], v45, v53, v[4:19]
	v_mfma_f32_32x32x2_f32 v[4:19], v46, v54, v[4:19]
	ds_read_b32 v43, v40 offset:10240
	v_and_b32_e32 v59, 0x7f, v42
	v_lshl_add_u32 v59, v59, 2, s5
	ds_read_b32 v51, v59
	v_add_u32_e32 v42, v42, v41
	ds_read_b32 v44, v40 offset:10496
	v_and_b32_e32 v59, 0x7f, v42
	v_lshl_add_u32 v59, v59, 2, s5
	ds_read_b32 v52, v59
	v_add_u32_e32 v42, v42, v41
	ds_read_b32 v45, v40 offset:10752
	v_and_b32_e32 v59, 0x7f, v42
	v_lshl_add_u32 v59, v59, 2, s5
	ds_read_b32 v53, v59
	v_add_u32_e32 v42, v42, v41
	ds_read_b32 v46, v40 offset:11008
	v_and_b32_e32 v59, 0x7f, v42
	v_lshl_add_u32 v59, v59, 2, s5
	ds_read_b32 v54, v59
	v_add_u32_e32 v42, v42, v41
	s_waitcnt lgkmcnt(8)
	v_mfma_f32_32x32x2_f32 v[4:19], v47, v55, v[4:19]
	v_mfma_f32_32x32x2_f32 v[4:19], v48, v56, v[4:19]
	v_mfma_f32_32x32x2_f32 v[4:19], v49, v57, v[4:19]
	v_mfma_f32_32x32x2_f32 v[4:19], v50, v58, v[4:19]
	ds_read_b32 v47, v40 offset:11264
	v_and_b32_e32 v59, 0x7f, v42
	v_lshl_add_u32 v59, v59, 2, s5
	ds_read_b32 v55, v59
	v_add_u32_e32 v42, v42, v41
	ds_read_b32 v48, v40 offset:11520
	v_and_b32_e32 v59, 0x7f, v42
	v_lshl_add_u32 v59, v59, 2, s5
	ds_read_b32 v56, v59
	v_add_u32_e32 v42, v42, v41
	ds_read_b32 v49, v40 offset:11776
	v_and_b32_e32 v59, 0x7f, v42
	v_lshl_add_u32 v59, v59, 2, s5
	ds_read_b32 v57, v59
	v_add_u32_e32 v42, v42, v41
	ds_read_b32 v50, v40 offset:12032
	v_and_b32_e32 v59, 0x7f, v42
	v_lshl_add_u32 v59, v59, 2, s5
	ds_read_b32 v58, v59
	v_add_u32_e32 v42, v42, v41
	s_waitcnt lgkmcnt(8)
	v_mfma_f32_32x32x2_f32 v[4:19], v43, v51, v[4:19]
	v_mfma_f32_32x32x2_f32 v[4:19], v44, v52, v[4:19]
	v_mfma_f32_32x32x2_f32 v[4:19], v45, v53, v[4:19]
	v_mfma_f32_32x32x2_f32 v[4:19], v46, v54, v[4:19]
	ds_read_b32 v43, v40 offset:12288
	v_and_b32_e32 v59, 0x7f, v42
	v_lshl_add_u32 v59, v59, 2, s5
	ds_read_b32 v51, v59
	v_add_u32_e32 v42, v42, v41
	ds_read_b32 v44, v40 offset:12544
	v_and_b32_e32 v59, 0x7f, v42
	v_lshl_add_u32 v59, v59, 2, s5
	ds_read_b32 v52, v59
	v_add_u32_e32 v42, v42, v41
	ds_read_b32 v45, v40 offset:12800
	v_and_b32_e32 v59, 0x7f, v42
	v_lshl_add_u32 v59, v59, 2, s5
	ds_read_b32 v53, v59
	v_add_u32_e32 v42, v42, v41
	ds_read_b32 v46, v40 offset:13056
	v_and_b32_e32 v59, 0x7f, v42
	v_lshl_add_u32 v59, v59, 2, s5
	ds_read_b32 v54, v59
	v_add_u32_e32 v42, v42, v41
	s_waitcnt lgkmcnt(8)
	v_mfma_f32_32x32x2_f32 v[4:19], v47, v55, v[4:19]
	v_mfma_f32_32x32x2_f32 v[4:19], v48, v56, v[4:19]
	v_mfma_f32_32x32x2_f32 v[4:19], v49, v57, v[4:19]
	v_mfma_f32_32x32x2_f32 v[4:19], v50, v58, v[4:19]
	ds_read_b32 v47, v40 offset:13312
	v_and_b32_e32 v59, 0x7f, v42
	v_lshl_add_u32 v59, v59, 2, s5
	ds_read_b32 v55, v59
	v_add_u32_e32 v42, v42, v41
	ds_read_b32 v48, v40 offset:13568
	v_and_b32_e32 v59, 0x7f, v42
	v_lshl_add_u32 v59, v59, 2, s5
	ds_read_b32 v56, v59
	v_add_u32_e32 v42, v42, v41
	ds_read_b32 v49, v40 offset:13824
	v_and_b32_e32 v59, 0x7f, v42
	v_lshl_add_u32 v59, v59, 2, s5
	ds_read_b32 v57, v59
	v_add_u32_e32 v42, v42, v41
	ds_read_b32 v50, v40 offset:14080
	v_and_b32_e32 v59, 0x7f, v42
	v_lshl_add_u32 v59, v59, 2, s5
	ds_read_b32 v58, v59
	v_add_u32_e32 v42, v42, v41
	s_waitcnt lgkmcnt(8)
	v_mfma_f32_32x32x2_f32 v[4:19], v43, v51, v[4:19]
	v_mfma_f32_32x32x2_f32 v[4:19], v44, v52, v[4:19]
	v_mfma_f32_32x32x2_f32 v[4:19], v45, v53, v[4:19]
	v_mfma_f32_32x32x2_f32 v[4:19], v46, v54, v[4:19]
	ds_read_b32 v43, v40 offset:14336
	v_and_b32_e32 v59, 0x7f, v42
	v_lshl_add_u32 v59, v59, 2, s5
	ds_read_b32 v51, v59
	v_add_u32_e32 v42, v42, v41
	ds_read_b32 v44, v40 offset:14592
	v_and_b32_e32 v59, 0x7f, v42
	v_lshl_add_u32 v59, v59, 2, s5
	ds_read_b32 v52, v59
	v_add_u32_e32 v42, v42, v41
	ds_read_b32 v45, v40 offset:14848
	v_and_b32_e32 v59, 0x7f, v42
	v_lshl_add_u32 v59, v59, 2, s5
	ds_read_b32 v53, v59
	v_add_u32_e32 v42, v42, v41
	ds_read_b32 v46, v40 offset:15104
	v_and_b32_e32 v59, 0x7f, v42
	v_lshl_add_u32 v59, v59, 2, s5
	ds_read_b32 v54, v59
	v_add_u32_e32 v42, v42, v41
	s_waitcnt lgkmcnt(8)
	v_mfma_f32_32x32x2_f32 v[4:19], v47, v55, v[4:19]
	v_mfma_f32_32x32x2_f32 v[4:19], v48, v56, v[4:19]
	v_mfma_f32_32x32x2_f32 v[4:19], v49, v57, v[4:19]
	v_mfma_f32_32x32x2_f32 v[4:19], v50, v58, v[4:19]
	ds_read_b32 v47, v40 offset:15360
	v_and_b32_e32 v59, 0x7f, v42
	v_lshl_add_u32 v59, v59, 2, s5
	ds_read_b32 v55, v59
	v_add_u32_e32 v42, v42, v41
	ds_read_b32 v48, v40 offset:15616
	v_and_b32_e32 v59, 0x7f, v42
	v_lshl_add_u32 v59, v59, 2, s5
	ds_read_b32 v56, v59
	v_add_u32_e32 v42, v42, v41
	ds_read_b32 v49, v40 offset:15872
	v_and_b32_e32 v59, 0x7f, v42
	v_lshl_add_u32 v59, v59, 2, s5
	ds_read_b32 v57, v59
	v_add_u32_e32 v42, v42, v41
	ds_read_b32 v50, v40 offset:16128
	v_and_b32_e32 v59, 0x7f, v42
	v_lshl_add_u32 v59, v59, 2, s5
	ds_read_b32 v58, v59
	v_add_u32_e32 v42, v42, v41
	s_waitcnt lgkmcnt(8)
	v_mfma_f32_32x32x2_f32 v[4:19], v43, v51, v[4:19]
	v_mfma_f32_32x32x2_f32 v[4:19], v44, v52, v[4:19]
	v_mfma_f32_32x32x2_f32 v[4:19], v45, v53, v[4:19]
	v_mfma_f32_32x32x2_f32 v[4:19], v46, v54, v[4:19]
	s_waitcnt lgkmcnt(0)
	v_mfma_f32_32x32x2_f32 v[4:19], v47, v55, v[4:19]
	v_mfma_f32_32x32x2_f32 v[4:19], v48, v56, v[4:19]
	v_mfma_f32_32x32x2_f32 v[4:19], v49, v57, v[4:19]
	v_mfma_f32_32x32x2_f32 v[4:19], v50, v58, v[4:19]
	s_nop 7
	s_lshl_b32 s5, s27, 5
	s_and_b32 s5, s5, 0x60
	s_and_b32 s4, s26, 0x180
	v_or_b32_e32 v2, s5, v26
	s_mul_hi_i32 s5, s88, 0x2200000
	s_mul_i32 s88, s88, 0x2200000
	s_add_u32 s6, s10, s88
	s_addc_u32 s5, s11, s5
	s_lshl_b32 s7, s27, 11
	s_and_b32 s7, s7, 0x100000
	s_add_u32 s6, s6, s7
	s_addc_u32 s5, s5, 0
	s_lshl_b32 s4, s4, 1
	s_add_u32 s4, s6, s4
	s_addc_u32 s5, s5, 0
	v_lshlrev_b32_e32 v2, 1, v2
	v_lshl_add_u64 v[22:23], s[4:5], 0, v[2:3]
	s_lshl_b32 s4, s27, 13
	s_and_b32 s4, s4, 0xf8000
	v_lshl_or_b32 v2, v27, 1, s4
	v_lshl_add_u64 v[22:23], v[22:23], 0, v[2:3]
	s_mov_b64 s[4:5], 0x1980000
	v_lshl_add_u64 v[24:25], v[22:23], 0, s[4:5]
	s_mov_b32 s4, 0x1980000
	v_bfe_u32 v2, v4, 16, 1
	v_add_co_u32_e32 v38, vcc, s4, v22
	v_add3_u32 v2, v4, v2, s37
	s_nop 0
	v_addc_co_u32_e32 v39, vcc, 0, v23, vcc
	global_store_short_d16_hi v[38:39], v2, off
	v_bfe_u32 v2, v5, 16, 1
	v_add3_u32 v2, v5, v2, s37
	global_store_short_d16_hi v[24:25], v2, off offset:1024
	v_bfe_u32 v2, v6, 16, 1
	v_add3_u32 v2, v6, v2, s37
	global_store_short_d16_hi v[24:25], v2, off offset:2048
	v_bfe_u32 v2, v7, 16, 1
	v_add3_u32 v2, v7, v2, s37
	s_mov_b32 s4, 0x1982000
	global_store_short_d16_hi v[24:25], v2, off offset:3072
	v_bfe_u32 v2, v8, 16, 1
	v_add_co_u32_e32 v4, vcc, s4, v22
	v_add3_u32 v2, v8, v2, s37
	s_nop 0
	v_addc_co_u32_e32 v5, vcc, 0, v23, vcc
	global_store_short_d16_hi v[4:5], v2, off
	v_bfe_u32 v2, v9, 16, 1
	v_add3_u32 v2, v9, v2, s37
	global_store_short_d16_hi v[4:5], v2, off offset:1024
	v_bfe_u32 v2, v10, 16, 1
	v_add3_u32 v2, v10, v2, s37
	global_store_short_d16_hi v[4:5], v2, off offset:2048
	v_bfe_u32 v2, v11, 16, 1
	v_add3_u32 v2, v11, v2, s37
	s_mov_b32 s4, 0x1984000
	global_store_short_d16_hi v[4:5], v2, off offset:3072
	v_bfe_u32 v2, v12, 16, 1
	v_add_co_u32_e32 v4, vcc, s4, v22
	v_add3_u32 v2, v12, v2, s37
	s_nop 0
	v_addc_co_u32_e32 v5, vcc, 0, v23, vcc
	global_store_short_d16_hi v[4:5], v2, off
	v_bfe_u32 v2, v13, 16, 1
	v_add3_u32 v2, v13, v2, s37
	global_store_short_d16_hi v[4:5], v2, off offset:1024
	v_bfe_u32 v2, v14, 16, 1
	v_add3_u32 v2, v14, v2, s37
	global_store_short_d16_hi v[4:5], v2, off offset:2048
	v_bfe_u32 v2, v15, 16, 1
	v_add3_u32 v2, v15, v2, s37
	s_mov_b32 s4, 0x1986000
	global_store_short_d16_hi v[4:5], v2, off offset:3072
	v_bfe_u32 v2, v16, 16, 1
	v_add_co_u32_e32 v4, vcc, s4, v22
	v_add3_u32 v2, v16, v2, s37
	s_nop 0
	v_addc_co_u32_e32 v5, vcc, 0, v23, vcc
	global_store_short_d16_hi v[4:5], v2, off
	v_bfe_u32 v2, v17, 16, 1
	v_add3_u32 v2, v17, v2, s37
	global_store_short_d16_hi v[4:5], v2, off offset:1024
	v_bfe_u32 v2, v18, 16, 1
	v_add3_u32 v2, v18, v2, s37
	global_store_short_d16_hi v[4:5], v2, off offset:2048
	v_bfe_u32 v2, v19, 16, 1
	s_add_i32 s26, s26, s85
	s_add_i32 s20, s20, s85
	v_add3_u32 v2, v19, v2, s37
	s_cmpk_gt_i32 s26, 0x7ff
	global_store_short_d16_hi v[4:5], v2, off offset:3072
	s_cbranch_scc0 .LBB0_1865
